# FIX write-after-read race of the hoisted seam (Y overlays XN): mixer-A units reordered (both map-1 units first) and one wait on the all-GEMM-done counter before the first map-2 unit
# baseline (speedup 1.0000x reference)
; __global__ void __launch_bounds__(NWAVES * 64, 2) mega_fwd(Args a) {
;     ...
;         for (int i = 0;; ++i) {
;             int bh, qb;
;             if (G == 256) { if (i >= 4) break; bh = vcu >> 4; const int s = vcu & 15; qb = (i < 2) ? s : 31 - s; }
;             else { const int p = (i >> 1) * G + bx; if (p >= 512) break; bh = p >> 5; qb = 31 - (p & 31); }
;             const int b = bh >> 3, h = bh & 7, c = i & 1, hq = 2 * h + c;
.LBB0_182:
	s_cmp_lt_u32 s79, 4
	s_cbranch_scc0 .LBB0_184
	s_bitcmp0_b32 s79, 0
	v_readlane_b32 s0, v254, 58
	v_readlane_b32 s1, v254, 59
	s_cselect_b32 s92, s0, s1
	s_mov_b64 s[0:1], -1

;   #define DMA_K(t,slot) glds16(Kh+(long)(t)*KVBLK*KVP,koff,(unsigned)__builtin_amdgcn_readfirstlane(kdst+(slot)))
; template<int THRL,int MODE,int KVP,int DV,bool FAST> __device__ __forceinline__ void attn_unit(int b,int qb,const bf16*Qh,const bf16*__restrict__ Kh0,const bf16*__restrict__ Vh0,bf16*Oh,float sink_l2,const EpiArgs ea,char*shm){
;     ...
;   const int tid=threadIdx.x,lane=tid&63,r32=lane&31,hi=lane>>5; const int wid=__builtin_amdgcn_readfirstlane(tid>>6);
;   const long rowbase=(long)b*SEQ; const int q0=qb*QB;
;   const bf16*Qw=Qh+(rowbase+q0+wid*QBLK)*QP;
;   const int t0=(MODE==1&&qb>0)?4*qb-2:0;     const bf16*Kh=Kh0+(rowbase+(long)t0*KVBLK)*KVP,*Vh=Vh0+(rowbase+(long)t0*KVBLK)*KVP;
;   const unsigned lds0=(unsigned)(uintptr_t)shm;
;   float*wsf=(float*)(shm+LDS_WS)+wid*64;
;   const unsigned koff=(unsigned)(lane*KVP+wid*8)*2u;
;   const unsigned voff=(unsigned)((16*(wid&3)+(lane>>2))*KVP+(wid>>2)*32+(lane&3)*8)*2u;
;   const unsigned kdst=lds0+LDS_K+wid*1024, vdst=lds0+LDS_V+wid*1024;
;     ...
;   const int vb0=(int)(lds0+LDS_V)+((lane>>4)&1)*32+(lane&3)*8+(4*hi+((lane&15)>>2))*64;
;   const char*Kbase=shm+LDS_K; bf16x8 kf[8];
;   const lds_cptr shm3=(lds_cptr)shm; const lds_cptr kp0=shm3+LDS_K+hi*1024+r32*16; const lds_cptr vp0=shm3+LDS_V+((lane>>4)&1)*32+(lane&3)*8+(4*hi+((lane&15)>>2))*64;
;   const int NT=(MODE==1)?((qb>0)?6:4):(q0+QB)/KVBLK;
;   DMA_K(0,0);DMA_V(0,0);DMA_K(1,SLOTB);
;   bf16x8 qr[4];
;   #pragma unroll
;   for(int d0=0;d0<4;++d0)qr[d0]=*reinterpret_cast<const bf16x8*>(&Qw[(long)r32*QP+d0*16+hi*8]);
; __global__ void __launch_bounds__(NWAVES * 64, 2) mega_fwd(Args a) {
;     ...
;             if (G == 256) { if (i >= 4) break; bh = vcu >> 4; const int s = vcu & 15; qb = (i < 2) ? s : 31 - s; }
;             else { const int p = (i >> 1) * G + bx; if (p >= 512) break; bh = p >> 5; qb = 31 - (p & 31); }
;             const int b = bh >> 3, h = bh & 7, c = i & 1, hq = 2 * h + c;
;             const attn_body::EpiArgs ea{c, (const abf*)GA + h * 128, (abf*)Y + h * 128, a.subw, a.lq1, a.lk1, a.lq2, a.lk2};
;             if (fastA) attn_body::attn_unit<8, 0, 1024, 128, true>(b, qb, (const abf*)QA + hq * 64, (const abf*)KA + hq * 64, (const abf*)VA + h * 128, (abf*)OA1 + h * 128, 0.f, ea, shm);
.LBB0_185:
	s_cmp_lg_u32 s79, 2
	s_cbranch_scc1 .Lyw_skip
	v_readlane_b32 s100, v254, 61
	v_readlane_b32 s101, v254, 62
	v_mov_b32_e32 v249, 0
	s_nop 4
.Lyw_loop:
	global_load_dword v252, v249, s[100:101] offset:260 sc1
	s_waitcnt vmcnt(0)
	v_readfirstlane_b32 s32, v252
	s_nop 3
	s_cmp_lt_u32 s32, s83
	s_cbranch_scc0 .Lyw_skip
	s_sleep 2
	s_branch .Lyw_loop
.Lyw_skip:
	s_lshl_b32 s1, s68, 8
	s_ashr_i32 s0, s68, 3
	s_lshr_b32 s98, s79, 1
	s_and_b32 s1, s1, 0x700
	v_readlane_b32 s2, v254, 20
	s_add_u32 s2, s2, s1
	s_nop 0
	v_writelane_b32 v255, s2, 10
	v_readlane_b32 s2, v254, 21
	s_addc_u32 s2, s2, 0
	s_nop 0
	v_writelane_b32 v255, s2, 11
	s_add_u32 s2, s80, s1
	v_writelane_b32 v255, s2, 12
	s_addc_u32 s2, s81, 0
	v_writelane_b32 v255, s2, 13
	s_lshl_b32 s2, s98, 7
	s_or_b32 s2, s2, s1
	s_add_u32 s8, s74, s2
	s_addc_u32 s9, s75, 0
	s_add_u32 s4, s16, s2
	s_addc_u32 s5, s17, 0
	v_readlane_b32 s2, v254, 18
	s_add_u32 s6, s2, s1
	v_readlane_b32 s2, v254, 19
	s_addc_u32 s7, s2, 0
	s_add_u32 s93, s94, s1
	s_addc_u32 s97, s69, 0
	s_ashr_i32 s1, s0, 31
	s_lshl_b64 s[2:3], s[0:1], 13
	s_lshl_b32 s95, s92, 8
	s_add_u32 s10, s2, s95
	s_addc_u32 s11, s3, 0
	s_lshl_b64 s[74:75], s[0:1], 24
	s_add_u32 s66, s4, s74
	s_addc_u32 s67, s5, s75
	v_readlane_b32 s2, v254, 54
	s_add_u32 s90, s6, s74
	v_readlane_b32 s3, v254, 55
	s_addc_u32 s91, s7, s75
	s_mov_b64 s[0:1], -1
	s_and_b64 vcc, exec, s[2:3]
	s_cbranch_vccz .LBB0_271
	v_readfirstlane_b32 s31, v229
	s_lshr_b32 s3, s31, 6
	s_lshl_b32 s70, s3, 5
	s_add_u32 s0, s10, s70
	s_addc_u32 s1, s11, 0
	v_writelane_b32 v255, s0, 14
	v_lshlrev_b32_e32 v13, 1, v228
	v_mov_b32_e32 v2, v0
	v_writelane_b32 v255, s1, 15
	s_lshl_b64 s[0:1], s[0:1], 11
	s_add_u32 s0, s8, s0
	s_addc_u32 s1, s9, s1
	s_lshl_b32 s2, s3, 4
	v_add_u32_e32 v250, s2, v245
	v_and_or_b32 v1, s2, 48, v233
	s_lshr_b32 s2, s31, 3
	s_and_b32 s2, s2, 0x1fffffe0
	s_lshl_b32 s30, s3, 10
	s_cmp_lg_u32 0, -1
	v_lshl_add_u32 v1, v1, 10, s2
	s_cselect_b32 s2, 0, 0
	v_or_b32_e32 v1, v1, v234
	s_add_i32 s84, s30, s2
	s_mov_b32 s2, m0
	s_mov_b32 m0, s84
	s_nop 0
	global_load_lds_dwordx4 v250, s[66:67]
	s_mov_b32 m0, s2
	v_lshlrev_b32_e32 v251, 1, v1
	s_add_i32 s73, s84, 0x6000
	s_mov_b32 s2, m0
	s_mov_b32 m0, s73
	s_nop 0
	global_load_lds_dwordx4 v251, s[90:91]
	s_mov_b32 m0, s2
	s_add_u32 s2, s90, 0x80
	v_writelane_b32 v255, s3, 16
	s_addc_u32 s3, s91, 0
	s_add_i32 s4, s84, 0x8000
	s_mov_b32 s5, m0
	s_mov_b32 m0, s4
	s_nop 0
	global_load_lds_dwordx4 v251, s[2:3]
	s_mov_b32 m0, s5
	s_add_u32 s2, s66, 0x20000
	s_addc_u32 s3, s67, 0
	s_add_i32 s4, s84, 0x2000
	s_mov_b32 s5, m0
	s_mov_b32 m0, s4
	s_nop 0
	global_load_lds_dwordx4 v250, s[2:3]
	s_mov_b32 m0, s5
	global_load_dwordx4 v[172:175], v13, s[0:1]
	global_load_dwordx4 v[168:171], v13, s[0:1] offset:32
	global_load_dwordx4 v[160:163], v13, s[0:1] offset:64
	global_load_dwordx4 v[152:155], v13, s[0:1] offset:96
	v_mov_b32_e32 v3, v0
	v_mov_b32_e32 v4, v0
	v_mov_b32_e32 v5, v0
	v_mov_b32_e32 v6, v0
	v_mov_b32_e32 v7, v0
	v_mov_b32_e32 v8, v0
	v_mov_b32_e32 v9, v0
	v_mov_b32_e32 v10, v0
	v_mov_b32_e32 v11, v0
	v_mov_b32_e32 v12, v0
	v_mov_b32_e32 v13, v0
	v_mov_b32_e32 v14, v0
	v_mov_b32_e32 v15, v0
	v_mov_b32_e32 v1, v0
	v_mov_b64_e32 v[16:17], v[14:15]
	v_mov_b64_e32 v[14:15], v[12:13]
	v_mov_b64_e32 v[12:13], v[10:11]
	v_mov_b64_e32 v[10:11], v[8:9]
	v_mov_b64_e32 v[8:9], v[6:7]
	v_mov_b64_e32 v[6:7], v[4:5]
	v_mov_b64_e32 v[4:5], v[2:3]
	v_mov_b64_e32 v[2:3], v[0:1]
	s_add_u32 s0, s66, 0x40000
	s_addc_u32 s1, s67, 0
	s_add_i32 s2, s84, 0x4000
	s_mov_b32 s3, m0
	s_mov_b32 m0, s2
	s_nop 0
	global_load_lds_dwordx4 v250, s[0:1]
	s_mov_b32 m0, s3
	s_waitcnt vmcnt(4) lgkmcnt(0)
	s_barrier
; #define WAIT_BAR(N) asm volatile("s_waitcnt vmcnt(%c0) lgkmcnt(0)\n\ts_barrier"::"n"(N):"memory")
;   #define DMA_K(t,slot) glds16(Kh+(long)(t)*KVBLK*KVP,koff,(unsigned)__builtin_amdgcn_readfirstlane(kdst+(slot)))
;   #define CMASK(P0,P1,t) do{ if(MODE==1){ smask(P0,P1,64*((t)+t0)-q0,qrel,hi); } else { int jb_=(t)-(NT-4); if(jb_>=0)cmask(P0,P1,jb_,qrel,hi);} }while(0)
;   #define CMASK(P0,P1,t) do{}while(0)
;   #define CMASK(P0,P1,t) do{ if(MODE==1){ smask(P0,P1,64*((t)+t0)-q0,qrel,hi); } else { int jb_=(t)-(NT-4); if(jb_>=0)cmask(P0,P1,jb_,qrel,hi);} }while(0)
; __device__ __forceinline__ void qkt(f32x16&p0,f32x16&p1,const char*Kslot,const bf16x8*qr,const f32x16&negm,int r32,int hi){
;   const char*kb=Kslot+hi*1024+r32*16;
;   #pragma unroll
;   for(int d0=0;d0<4;++d0){
;     const bf16x8 b0=*reinterpret_cast<const bf16x8*>(kb+d0*2048);
;     const bf16x8 b1=*reinterpret_cast<const bf16x8*>(kb+d0*2048+512);
;     if(d0==0){p0=__builtin_amdgcn_mfma_f32_32x32x16_bf16(b0,qr[0],negm,0,0,0);p1=__builtin_amdgcn_mfma_f32_32x32x16_bf16(b1,qr[0],negm,0,0,0);}
;     else{p0=__builtin_amdgcn_mfma_f32_32x32x16_bf16(b0,qr[d0],p0,0,0,0);p1=__builtin_amdgcn_mfma_f32_32x32x16_bf16(b1,qr[d0],p1,0,0,0);}}
; }
; template<int THRL,int MODE,int KVP,int DV,bool FAST> __device__ __forceinline__ void attn_unit(int b,int qb,const bf16*Qh,const bf16*__restrict__ Kh0,const bf16*__restrict__ Vh0,bf16*Oh,float sink_l2,const EpiArgs ea,char*shm){
;     ...
;   DMA_K(2,2*SLOTB);
;   WAIT_BAR(2+NV);
;   qkt(pA0,pA1,Kbase,qr,negm,r32,hi);asm volatile("s_nop 15\n\ts_nop 7":"+v"(pA0),"+v"(pA1));CMASK(pA0,pA1,0);
	ds_read_b128 v[34:37], v237
	v_writelane_b32 v255, s8, 17
	s_cmp_lg_u32 s92, 0
	v_writelane_b32 v255, s9, 18
	v_or_b32_e32 v1, s70, v232
	s_cselect_b64 s[0:1], -1, 0
	v_writelane_b32 v255, s10, 19
	v_sub_u32_e32 v249, v1, v238
	s_and_b64 vcc, exec, s[0:1]
	v_writelane_b32 v255, s11, 20
	s_waitcnt vmcnt(3) lgkmcnt(0)
	v_mfma_f32_32x32x16_bf16 v[18:33], v[34:37], v[172:175], v[2:17]
	ds_read_b128 v[34:37], v237 offset:512
	s_waitcnt lgkmcnt(0)
	v_mfma_f32_32x32x16_bf16 v[2:17], v[34:37], v[172:175], v[2:17]
	ds_read_b128 v[34:37], v237 offset:2048
	s_waitcnt vmcnt(2) lgkmcnt(0)
	v_mfma_f32_32x32x16_bf16 v[18:33], v[34:37], v[168:171], v[18:33]
	ds_read_b128 v[34:37], v237 offset:2560
	s_waitcnt lgkmcnt(0)
	v_mfma_f32_32x32x16_bf16 v[2:17], v[34:37], v[168:171], v[2:17]
	ds_read_b128 v[34:37], v237 offset:4096
	s_waitcnt vmcnt(1) lgkmcnt(0)
	v_mfma_f32_32x32x16_bf16 v[18:33], v[34:37], v[160:163], v[18:33]
	ds_read_b128 v[34:37], v237 offset:4608
	s_waitcnt lgkmcnt(0)
	v_mfma_f32_32x32x16_bf16 v[2:17], v[34:37], v[160:163], v[2:17]
	ds_read_b128 v[34:37], v237 offset:6144
	s_waitcnt vmcnt(0) lgkmcnt(0)
	v_mfma_f32_32x32x16_bf16 v[18:33], v[34:37], v[152:155], v[18:33]
	ds_read_b128 v[34:37], v237 offset:6656
	s_waitcnt lgkmcnt(0)
	v_mfma_f32_32x32x16_bf16 v[2:17], v[34:37], v[152:155], v[2:17]
	s_nop 15
	s_nop 7
	s_cbranch_vccnz .LBB0_188
	v_mov_b32_e32 v1, v249
	s_nop 0
	v_cmp_gt_i32_e64 s[62:63], 26, v1
	v_cmp_gt_i32_e64 s[64:65], 27, v1
	v_cmp_gt_i32_e64 s[60:61], 25, v1
	s_and_b64 s[62:63], s[64:65], s[62:63]
	v_cmp_gt_i32_e64 s[58:59], 24, v1
	s_and_b64 s[60:61], s[62:63], s[60:61]
	v_cmp_gt_i32_e64 s[56:57], 19, v1
	s_and_b64 s[58:59], s[60:61], s[58:59]
	v_cmp_gt_i32_e64 s[54:55], 18, v1
	s_and_b64 s[56:57], s[58:59], s[56:57]
	v_cmp_gt_i32_e64 s[52:53], 17, v1
	s_and_b64 s[54:55], s[56:57], s[54:55]
	v_cmp_gt_i32_e64 s[50:51], 16, v1
	s_and_b64 s[52:53], s[54:55], s[52:53]
	v_cmp_gt_i32_e64 s[48:49], 11, v1
	s_and_b64 s[50:51], s[52:53], s[50:51]
	v_cmp_gt_i32_e64 s[46:47], 10, v1
	s_and_b64 s[48:49], s[50:51], s[48:49]
	v_cmp_gt_i32_e64 s[44:45], 9, v1
	s_and_b64 s[46:47], s[48:49], s[46:47]
	v_cmp_gt_i32_e64 s[42:43], 8, v1
	s_and_b64 s[44:45], s[46:47], s[44:45]
	v_cmp_gt_i32_e64 s[40:41], 3, v1
	s_and_b64 s[42:43], s[44:45], s[42:43]
	v_cmp_gt_i32_e64 s[38:39], 2, v1
	s_and_b64 s[40:41], s[42:43], s[40:41]
	v_cmp_gt_i32_e64 s[36:37], 1, v1
	s_and_b64 s[38:39], s[40:41], s[38:39]
	v_cmp_gt_i32_e64 s[34:35], 0, v1
	s_and_b64 s[36:37], s[38:39], s[36:37]
	s_and_b64 s[34:35], s[36:37], s[34:35]
	v_cmp_gt_i32_e64 s[28:29], 58, v1
	v_cndmask_b32_e64 v18, v18, v248, s[34:35]
	v_cmp_gt_i32_e64 s[34:35], 59, v1
	v_cmp_gt_i32_e64 s[26:27], 57, v1
	s_and_b64 s[28:29], s[34:35], s[28:29]
	v_cmp_gt_i32_e64 s[24:25], 56, v1
	s_and_b64 s[26:27], s[28:29], s[26:27]
	v_cmp_gt_i32_e64 s[22:23], 51, v1
	s_and_b64 s[24:25], s[26:27], s[24:25]
	v_cmp_gt_i32_e64 s[20:21], 50, v1
	s_and_b64 s[22:23], s[24:25], s[22:23]
	v_cmp_gt_i32_e64 s[18:19], 49, v1
	s_and_b64 s[20:21], s[22:23], s[20:21]
	v_cmp_gt_i32_e64 s[16:17], 48, v1
	s_and_b64 s[18:19], s[20:21], s[18:19]
	v_cmp_gt_i32_e64 s[14:15], 43, v1
	s_and_b64 s[16:17], s[18:19], s[16:17]
	v_cmp_gt_i32_e64 s[12:13], 42, v1
	s_and_b64 s[14:15], s[16:17], s[14:15]
	v_cmp_gt_i32_e64 s[10:11], 41, v1
	s_and_b64 s[12:13], s[14:15], s[12:13]
	v_cmp_gt_i32_e64 s[8:9], 40, v1
	s_and_b64 s[10:11], s[12:13], s[10:11]
	v_cmp_gt_i32_e64 s[6:7], 35, v1
	s_and_b64 s[8:9], s[10:11], s[8:9]
	v_cmp_gt_i32_e64 s[4:5], 34, v1
	s_and_b64 s[6:7], s[8:9], s[6:7]
	v_cmp_gt_i32_e64 s[2:3], 33, v1
	s_and_b64 s[4:5], s[6:7], s[4:5]
	v_cmp_gt_i32_e32 vcc, 32, v1
	s_and_b64 s[2:3], s[4:5], s[2:3]
	s_and_b64 vcc, s[2:3], vcc
	v_cndmask_b32_e64 v33, v33, v248, s[64:65]
	v_cndmask_b32_e64 v32, v32, v248, s[62:63]
	v_cndmask_b32_e64 v31, v31, v248, s[60:61]
	v_cndmask_b32_e64 v30, v30, v248, s[58:59]
	v_cndmask_b32_e64 v29, v29, v248, s[56:57]
	v_cndmask_b32_e64 v28, v28, v248, s[54:55]
	v_cndmask_b32_e64 v27, v27, v248, s[52:53]
	v_cndmask_b32_e64 v26, v26, v248, s[50:51]
	v_cndmask_b32_e64 v25, v25, v248, s[48:49]
	v_cndmask_b32_e64 v24, v24, v248, s[46:47]
	v_cndmask_b32_e64 v23, v23, v248, s[44:45]
	v_cndmask_b32_e64 v22, v22, v248, s[42:43]
	v_cndmask_b32_e64 v21, v21, v248, s[40:41]
	v_cndmask_b32_e64 v20, v20, v248, s[38:39]
	v_cndmask_b32_e64 v19, v19, v248, s[36:37]
	v_cndmask_b32_e64 v17, v17, v248, s[34:35]
	v_cndmask_b32_e64 v16, v16, v248, s[28:29]
	v_cndmask_b32_e64 v15, v15, v248, s[26:27]
	v_cndmask_b32_e64 v14, v14, v248, s[24:25]
	v_cndmask_b32_e64 v13, v13, v248, s[22:23]
	v_cndmask_b32_e64 v12, v12, v248, s[20:21]
	v_cndmask_b32_e64 v11, v11, v248, s[18:19]
	v_cndmask_b32_e64 v10, v10, v248, s[16:17]
	v_cndmask_b32_e64 v9, v9, v248, s[14:15]
	v_cndmask_b32_e64 v8, v8, v248, s[12:13]
	v_cndmask_b32_e64 v7, v7, v248, s[10:11]
	v_cndmask_b32_e64 v6, v6, v248, s[8:9]
	v_cndmask_b32_e64 v5, v5, v248, s[6:7]
	v_cndmask_b32_e64 v4, v4, v248, s[4:5]
	v_cndmask_b32_e64 v3, v3, v248, s[2:3]
	v_cndmask_b32_e32 v2, v2, v248, vcc
